# phase 0: Hyena filter-MLP items handed out from the highest-numbered workgroups (the lowest-numbered ones already carry the adaLN GEMV items)
# speedup vs baseline: 1.0496x; 1.0020x over previous
.LBB0_1076:
	s_or_b64 exec, exec, s[0:1]
	s_sub_i32 s0, 0xff, s2
	v_mov_b32_e32 v0, v196
	s_lshl_b32 s0, s0, 1
	v_readfirstlane_b32 s1, v0
	s_ashr_i32 s1, s1, 8
	v_mov_b32_e32 v0, v196
	s_add_i32 s1, s1, s0
	s_nop 0
	v_readfirstlane_b32 s0, v0
	s_ashr_i32 s0, s0, 8
	s_sub_i32 s29, s1, s0
	s_cmpk_gt_i32 s29, 0x47f
	s_cbranch_scc1 .LBB0_1115
	v_add_u32_e32 v0, -1, v39
	v_and_b32_e32 v0, 15, v0
	v_lshlrev_b32_e32 v6, 9, v40
	v_cvt_f32_ubyte0_e32 v0, v0
	v_mov_b32_e32 v4, 0x38d1b717
	v_readlane_b32 s4, v253, 6
	v_add_u32_e32 v15, s33, v6
	s_waitcnt vmcnt(0)
	v_fmamk_f32 v16, v0, 0x3f7fff90, v4
	v_lshlrev_b32_e32 v0, 1, v18
	v_readlane_b32 s5, v253, 7
	s_add_i32 s54, s33, 0x100
	v_cmp_gt_u32_e64 s[40:41], 33, v18
	v_cmp_ne_u32_e64 s[42:43], 0, v18
	v_cmp_lt_u32_e64 s[44:45], 16, v18
	v_mov_b32_e32 v19, v1
	v_lshl_add_u32 v17, v18, 2, v15
	v_lshl_add_u64 v[4:5], s[4:5], 0, v[0:1]
	v_add_u32_e32 v20, s54, v6
	v_lshlrev_b32_e32 v0, 2, v18
	v_readlane_b32 s6, v253, 8
	v_readlane_b32 s7, v253, 9
	s_branch .LBB0_1079
